# residual GEMM split-K tails (w_out_e, w_out_o, FF2) computed by a direct-from-global MFMA routine over all WGs instead of 256x256x256 tail units on 16-64 WGs
# baseline (speedup 1.0000x reference)
; #define PG8_LAS __attribute__((address_space(3)))
; DEVI int obid() { int t = blockIdx.x; asm volatile("" : "+s"(t)); return t; }
;     __device__ __forceinline__ void operator()(const f32x4 (&acc)[2][2][4][2], const Unit& u, int wr, int wc, int fr, int fq) const {
;         const int col0 = u.pn * BM + wc * 32 + 4 * fq;
; #pragma unroll
;         for (int m = 0; m < 4; ++m) { float* sp = slab + ((size_t)(ks * 128 + wr * 64 + m * 16 + fr)) * 1024 + col0;
; #pragma unroll
;             for (int bj = 0; bj < 2; ++bj)
; #pragma unroll
;                 for (int n = 0; n < 2; ++n) *(f32x4*)(sp + bj * HALF + n * 16) = acc[0][bj][m][n]; }
; template <bool FIRST>
; __device__ __forceinline__ void run_gemm_res(const Params& p, unsigned char* smem, const bf16_t* A, int lda, const bf16_t* Bt, int K) {
;     ...
;   { const int c = obid(), ks = c >> 2;
;     pg8::TailOrder TS{c, 4 * (K >> 8), 128};
;     pg8::Gemm g{A + ks * 256, Bt + ks * 256, MP, 1024, 256, lda, K};
;     pg8::gemm_phase<pg8::EpiSlab, pg8::TailOrder, true, true>((PG8_LAS unsigned char*)smem, g, TS, pg8::EpiSlab{(float*)(p.ws + OFF_SLAB), ks}); }
.LBB0_951:
	v_readlane_b32 s4, v253, 2
	v_readlane_b32 s6, v253, 4
	v_readlane_b32 s7, v253, 5
	s_add_u32 s0, s6, 0x1bb15900
	s_addc_u32 s1, s7, 0
	v_readlane_b32 s2, v254, 22
	v_writelane_b32 v254, s0, 25
	v_mov_b32_e32 v24, v128
	s_cmp_gt_i32 s2, 31
	v_writelane_b32 v254, s1, 26
	v_readfirstlane_b32 s29, v24
	v_readlane_b32 s64, v254, 0
	v_readlane_b32 s65, v254, 1
	v_readlane_b32 s5, v253, 3
	v_mov_b32_e32 v104, s27
	v_mov_b32_e32 v105, s28
	v_readlane_b32 s98, v253, 24
	v_readlane_b32 s99, v253, 26
	v_mov_b32_e32 v106, s98
	v_mov_b32_e32 v107, s99
	v_readlane_b32 s98, v254, 25
	v_readlane_b32 s99, v254, 26
	v_mov_b32_e32 v108, s98
	v_mov_b32_e32 v109, s99
	v_readlane_b32 s100, v254, 22
	s_cmp_ge_u32 s100, 0x100
	s_cbranch_scc1 .Lrte_done
	v_lshrrev_b32_e32 v110, 6, v128
	v_and_b32_e32 v111, 15, v128
	v_bfe_u32 v112, v128, 4, 2
	v_lshl_or_b32 v113, v110, 4, v111
	v_add_u32_e32 v114, 0x8000, v113
	v_mul_u32_u24_e32 v114, 0x2800, v114
	v_lshl_add_u32 v114, v112, 4, v114
	v_mul_u32_u24_e32 v115, 0x1000, v111
	v_lshl_add_u32 v115, v112, 4, v115
	v_lshlrev_b32_e32 v116, 12, v113
	v_lshl_add_u32 v116, v112, 4, v116
	v_mov_b32_e32 v119, 0
.Lrte_loop:
	s_lshr_b32 s101, s100, 5
	s_and_b32 s98, s100, 31
	s_lshl_b32 s99, s101, 9
	s_mul_i32 vcc_lo, s98, 0x20000
	s_add_i32 vcc_lo, vcc_lo, s99
	v_add_u32_e32 v118, s99, v114
	v_lshl_add_u64 v[120:121], v[104:105], 0, v[118:119]
	v_add_u32_e32 v118, vcc_lo, v115
	v_lshl_add_u64 v[122:123], v[106:107], 0, v[118:119]
	v_add_u32_e32 v118, 0x10000, v118
	v_lshl_add_u64 v[124:125], v[106:107], 0, v[118:119]
	s_lshl_b32 s99, s101, 19
	s_lshl_b32 s98, s98, 7
	s_add_i32 s99, s99, s98
	v_add_u32_e32 v118, s99, v116
	v_lshl_add_u64 v[126:127], v[108:109], 0, v[118:119]
	global_load_dwordx4 v[64:67], v[120:121], off
	global_load_dwordx4 v[0:3], v[122:123], off
	global_load_dwordx4 v[32:35], v[124:125], off
	global_load_dwordx4 v[68:71], v[120:121], off offset:64
	global_load_dwordx4 v[4:7], v[122:123], off offset:64
	global_load_dwordx4 v[36:39], v[124:125], off offset:64
	global_load_dwordx4 v[72:75], v[120:121], off offset:128
	global_load_dwordx4 v[8:11], v[122:123], off offset:128
	global_load_dwordx4 v[40:43], v[124:125], off offset:128
	global_load_dwordx4 v[76:79], v[120:121], off offset:192
	global_load_dwordx4 v[12:15], v[122:123], off offset:192
	global_load_dwordx4 v[44:47], v[124:125], off offset:192
	global_load_dwordx4 v[80:83], v[120:121], off offset:256
	global_load_dwordx4 v[16:19], v[122:123], off offset:256
	global_load_dwordx4 v[48:51], v[124:125], off offset:256
	global_load_dwordx4 v[84:87], v[120:121], off offset:320
	global_load_dwordx4 v[20:23], v[122:123], off offset:320
	global_load_dwordx4 v[52:55], v[124:125], off offset:320
	global_load_dwordx4 v[88:91], v[120:121], off offset:384
	global_load_dwordx4 v[24:27], v[122:123], off offset:384
	global_load_dwordx4 v[56:59], v[124:125], off offset:384
	global_load_dwordx4 v[92:95], v[120:121], off offset:448
	global_load_dwordx4 v[28:31], v[122:123], off offset:448
	global_load_dwordx4 v[60:63], v[124:125], off offset:448
	s_waitcnt vmcnt(21)
	v_mfma_f32_16x16x32_bf16 v[96:99], v[0:3], v[64:67], 0
	v_mfma_f32_16x16x32_bf16 v[100:103], v[32:35], v[64:67], 0
	s_waitcnt vmcnt(18)
	v_mfma_f32_16x16x32_bf16 v[96:99], v[4:7], v[68:71], v[96:99]
	v_mfma_f32_16x16x32_bf16 v[100:103], v[36:39], v[68:71], v[100:103]
	s_waitcnt vmcnt(15)
	v_mfma_f32_16x16x32_bf16 v[96:99], v[8:11], v[72:75], v[96:99]
	v_mfma_f32_16x16x32_bf16 v[100:103], v[40:43], v[72:75], v[100:103]
	s_waitcnt vmcnt(12)
	v_mfma_f32_16x16x32_bf16 v[96:99], v[12:15], v[76:79], v[96:99]
	v_mfma_f32_16x16x32_bf16 v[100:103], v[44:47], v[76:79], v[100:103]
	s_waitcnt vmcnt(9)
	v_mfma_f32_16x16x32_bf16 v[96:99], v[16:19], v[80:83], v[96:99]
	v_mfma_f32_16x16x32_bf16 v[100:103], v[48:51], v[80:83], v[100:103]
	s_waitcnt vmcnt(6)
	v_mfma_f32_16x16x32_bf16 v[96:99], v[20:23], v[84:87], v[96:99]
	v_mfma_f32_16x16x32_bf16 v[100:103], v[52:55], v[84:87], v[100:103]
	s_waitcnt vmcnt(3)
	v_mfma_f32_16x16x32_bf16 v[96:99], v[24:27], v[88:91], v[96:99]
	v_mfma_f32_16x16x32_bf16 v[100:103], v[56:59], v[88:91], v[100:103]
	s_waitcnt vmcnt(0)
	v_mfma_f32_16x16x32_bf16 v[96:99], v[28:31], v[92:95], v[96:99]
	v_mfma_f32_16x16x32_bf16 v[100:103], v[60:63], v[92:95], v[100:103]
	s_nop 15
	s_nop 7
	global_store_dwordx4 v[126:127], v[96:99], off
	global_store_dwordx4 v[126:127], v[100:103], off offset:64
	s_add_i32 s100, s100, s52
	s_cmp_lt_u32 s100, 0x100
	s_cbranch_scc1 .Lrte_loop
; DEVI int otid() { int t = threadIdx.x; asm volatile("" : "+v"(t)); return t; }
;     __device__ __forceinline__ bool next(int i, Unit& u) const { if (i != 0 || c >= n) return false; u.pm = pm; u.pn = c & 3; return true; }
; #define PG8_WAIT_V(n) asm volatile("s_waitcnt vmcnt(" #n ")" ::: "memory")
; #define PG8_BAR __builtin_amdgcn_s_barrier()
; template <class Epi, class Sched, bool ALIGN_EPI = false, bool SP2 = false>
; __device__ __forceinline__ void gemm_phase(PG8_LAS unsigned char* lds, const Gemm g, const Sched& S, const Epi& E) {
;     const int tid = otid(), wid = __builtin_amdgcn_readfirstlane(tid >> 6), lane = tid & 63, wr = wid >> 2, wc = wid & 3, fr = lane & 15, fq = lane >> 4;
;     const int K = g.K, nt = K / BK;
;     unsigned voffA[2], voffB[2];
; #pragma unroll
;     for (int i = 0; i < 2; ++i) { int R, C; stage_rc(tid * 16 + i * 8192, R, C); const int Rb = Epi::PERM ? ((R & ~31) + perm32(R & 31)) : R;
;         voffA[i] = (unsigned)(R * g.lda + C) * 2u; voffB[i] = (unsigned)(Rb * g.ldb + C) * 2u; }
;     const size_t kstep = (size_t)(BK * 2);
;     const size_t hstepA = (size_t)HALF * g.lda * 2, hstepB = (size_t)HALF * g.ldb * 2;
;     const size_t tstepA = 2 * hstepA, tstepB = 2 * hstepB;
;     const unsigned ldsw = (unsigned)wid * 1024u;
;     const int aoff = lds_byte(wr * 64 + fr, fq * 8), boff = lds_byte(wc * 32 + fr, fq * 8);
;     ...
;     Unit cur, nxt; int ui = 0;
;     if (!S.next(0, cur)) return;
;     f32x4 acc[2][2][4][2];
; #pragma unroll
;     for (int a = 0; a < 2; ++a)
; #pragma unroll
;         for (int b = 0; b < 2; ++b)
; #pragma unroll
;             for (int m = 0; m < 4; ++m)
; #pragma unroll
;                 for (int n = 0; n < 2; ++n) acc[a][b][m][n] = (f32x4){0.f, 0.f, 0.f, 0.f};
;     bf16x8 At[4][2], B0[2][2], B1[2][2];
;     const char* cA = (const char*)g.A + (size_t)cur.pm * tstepA; const char* cB = (const char*)g.Bt + (size_t)cur.pn * tstepB;
;     S.a_ready(cur);
;     if constexpr (SP2) {
;         PG8_STAGE(PG8_SB(0, 0), cB, voffB); PG8_STAGE(PG8_SB(0, 1), cB + hstepB, voffB); PG8_STAGE(PG8_SA(0, 0), cA, voffA); PG8_STAGE(PG8_SA(0, 1), cA + hstepA, voffA);
;         if (wr == 1) PG8_BAR;
;         PG8_WAIT_V(2); PG8_BAR;
;         PG8_STAGE(PG8_SB(1, 0), cB + kstep, voffB); PG8_STAGE(PG8_SA(1, 0), cA + kstep, voffA); PG8_STAGE(PG8_SB(1, 1), cB + hstepB + kstep, voffB);
;         PG8_WAIT_V(6); PG8_BAR;
.Lrte_done:
	s_branch .LBB0_957
	v_lshlrev_b32_e32 v1, 4, v24
	v_add_u32_e32 v0, 0x2000, v1
	v_ashrrev_i32_e32 v2, 31, v0
	v_lshrrev_b32_e32 v2, 22, v2
	v_add_u32_e32 v2, v0, v2
	v_ashrrev_i32_e32 v2, 10, v2
	v_mul_i32_i24_e32 v4, 0x400, v2
	v_sub_u32_e32 v0, v0, v4
	v_lshrrev_b32_e32 v4, 4, v0
	v_bitop3_b32 v0, v4, v0, 32 bitop3:0x6c
	s_ashr_i32 s13, s2, 2
	v_ashrrev_i32_e32 v4, 31, v0
	s_and_b32 s12, s2, 3
	s_lshl_b32 s2, s13, 8
	v_lshrrev_b32_e32 v4, 26, v4
	s_ashr_i32 s1, s29, 6
	s_ashr_i32 s3, s2, 31
	v_lshlrev_b32_e32 v3, 5, v2
	v_add_u32_e32 v4, v0, v4
	v_lshlrev_b32_e32 v2, 3, v2
	s_ashr_i32 s0, s29, 8
	s_lshl_b32 s14, s1, 10
	s_lshl_b64 s[2:3], s[2:3], 1
	v_readlane_b32 s4, v253, 24
	v_ashrrev_i32_e32 v5, 6, v4
	v_and_b32_e32 v2, -16, v2
	s_add_u32 s4, s4, s2
	v_readlane_b32 s5, v253, 26
	v_and_b32_e32 v4, 0xc0, v4
	v_add_u32_e32 v2, v5, v2
	v_bfe_i32 v5, v24, 27, 1
	s_addc_u32 s5, s5, s3
	v_sub_u32_e32 v0, v0, v4
	v_mov_b32_e32 v4, 1
	v_lshrrev_b32_e32 v5, 22, v5
	s_add_u32 s31, s27, s2
	v_and_b32_e32 v3, 32, v3
	v_ashrrev_i16_sdwa v0, v4, sext(v0) dst_sel:DWORD dst_unused:UNUSED_PAD src0_sel:DWORD src1_sel:BYTE_0
	s_movk_i32 s2, 0x1400
	v_add_u32_e32 v5, v1, v5
	v_add_u32_sdwa v0, v3, sext(v0) dst_sel:DWORD dst_unused:UNUSED_PAD src0_sel:DWORD src1_sel:WORD_0
	v_lshlrev_b32_e32 v3, 12, v2
	v_mul_lo_u32 v2, v2, s2
	v_and_b32_e32 v5, 0xfffffc00, v5
	v_lshl_add_u32 v8, v0, 1, v3
	v_add_lshl_u32 v0, v0, v2, 1
	v_ashrrev_i32_e32 v2, 31, v24
	v_sub_u32_e32 v1, v1, v5
	v_lshrrev_b32_e32 v2, 26, v2
	v_lshrrev_b32_e32 v5, 4, v1
	v_add_u32_e32 v2, v24, v2
	v_bitop3_b32 v5, v5, v1, 32 bitop3:0x6c
	v_ashrrev_i32_e32 v1, 31, v1
	v_ashrrev_i32_e32 v2, 6, v2
	v_lshrrev_b32_e32 v1, 26, v1
	v_lshlrev_b32_e32 v3, 5, v2
	v_add_u32_e32 v1, v5, v1
	v_lshlrev_b32_e32 v2, 3, v2
	v_ashrrev_i32_e32 v1, 6, v1
	v_and_b32_e32 v2, -16, v2
	v_mul_i32_i24_e32 v6, 64, v1
	v_add_u32_e32 v1, v1, v2
	s_addc_u32 s33, s28, s3
	v_sub_u32_e32 v5, v5, v6
	v_lshlrev_b32_e32 v2, 12, v1
	v_mul_lo_u32 v1, v1, s2
	s_lshl_b32 s2, s12, 20
	v_and_b32_e32 v3, 32, v3
	v_ashrrev_i16_sdwa v4, v4, sext(v5) dst_sel:DWORD dst_unused:UNUSED_PAD src0_sel:DWORD src1_sel:BYTE_0
	s_add_u32 s2, s4, s2
	v_add_u32_sdwa v3, v3, sext(v4) dst_sel:DWORD dst_unused:UNUSED_PAD src0_sel:DWORD src1_sel:WORD_0
	s_addc_u32 s3, s5, 0
	s_add_i32 s16, s14, 0x10000
	s_add_i32 s22, s14, 0x12000
	v_lshl_add_u32 v22, v3, 1, v2
	s_mov_b32 m0, s16
	s_add_u32 s4, s2, 0x80000
	global_load_lds_dwordx4 v22, s[2:3]
	s_mov_b32 m0, s22
	s_addc_u32 s5, s3, 0
	s_add_i32 s24, s14, 0x14000
	s_add_i32 s25, s14, 0x16000
	global_load_lds_dwordx4 v8, s[2:3]
	s_mov_b32 m0, s24
	s_add_u32 s6, s31, 0x14000000
	global_load_lds_dwordx4 v22, s[4:5]
	s_mov_b32 m0, s25
	s_addc_u32 s7, s33, 0
	s_add_i32 s28, s14, 0x2000
	v_add_lshl_u32 v6, v3, v1, 1
	global_load_lds_dwordx4 v8, s[4:5]
	s_mov_b32 m0, s14
	s_add_u32 s8, s31, 0x14140000
	global_load_lds_dwordx4 v6, s[6:7]
	s_mov_b32 m0, s28
	s_addc_u32 s9, s33, 0
	s_add_i32 s18, s14, 0x4000
	global_load_lds_dwordx4 v0, s[6:7]
	s_mov_b32 m0, s18
	s_add_i32 s20, s14, 0x6000
	global_load_lds_dwordx4 v6, s[8:9]
	s_mov_b32 m0, s20
	v_mov_b32_e32 v23, 0
	global_load_lds_dwordx4 v0, s[8:9]
	v_mov_b32_e32 v9, v23
	v_mov_b32_e32 v7, v23
	v_mov_b32_e32 v1, v23
	v_lshl_add_u64 v[18:19], s[2:3], 0, v[22:23]
	v_lshl_add_u64 v[20:21], s[2:3], 0, v[8:9]
	v_lshl_add_u64 v[16:17], s[4:5], 0, v[22:23]
	v_lshl_add_u64 v[10:11], s[4:5], 0, v[8:9]
	v_lshl_add_u64 v[12:13], s[6:7], 0, v[6:7]
	v_lshl_add_u64 v[14:15], s[6:7], 0, v[0:1]
	v_lshl_add_u64 v[2:3], s[8:9], 0, v[6:7]
	s_cmp_lg_u32 s0, 1
	v_lshl_add_u64 v[4:5], s[8:9], 0, v[0:1]
	s_cbranch_scc1 .LBB0_954
	s_barrier

; #define PG8_LAS __attribute__((address_space(3)))
; DEVI int obid() { int t = blockIdx.x; asm volatile("" : "+s"(t)); return t; }
;     __device__ __forceinline__ void operator()(const f32x4 (&acc)[2][2][4][2], const Unit& u, int wr, int wc, int fr, int fq) const {
;         const int col0 = u.pn * BM + wc * 32 + 4 * fq;
; #pragma unroll
;         for (int m = 0; m < 4; ++m) { float* sp = slab + ((size_t)(ks * 128 + wr * 64 + m * 16 + fr)) * 1024 + col0;
; #pragma unroll
;             for (int bj = 0; bj < 2; ++bj)
; #pragma unroll
;                 for (int n = 0; n < 2; ++n) *(f32x4*)(sp + bj * HALF + n * 16) = acc[0][bj][m][n]; }
; template <bool FIRST>
; __device__ __forceinline__ void run_gemm_res(const Params& p, unsigned char* smem, const bf16_t* A, int lda, const bf16_t* Bt, int K) {
;     ...
;   { const int c = obid(), ks = c >> 2;
;     pg8::TailOrder TS{c, 4 * (K >> 8), 128};
;     pg8::Gemm g{A + ks * 256, Bt + ks * 256, MP, 1024, 256, lda, K};
;     pg8::gemm_phase<pg8::EpiSlab, pg8::TailOrder, true, true>((PG8_LAS unsigned char*)smem, g, TS, pg8::EpiSlab{(float*)(p.ws + OFF_SLAB), ks}); }
.LBB0_2022:
	v_readlane_b32 s0, v254, 22
	s_waitcnt vmcnt(0)
	v_mov_b32_e32 v20, v128
	s_cmp_gt_i32 s0, 15
	v_readfirstlane_b32 s45, v20
	v_readlane_b32 s98, v254, 18
	v_readlane_b32 s99, v254, 19
	v_mov_b32_e32 v104, s98
	v_mov_b32_e32 v105, s99
	v_readlane_b32 s98, v254, 8
	v_readlane_b32 s99, v254, 9
	v_mov_b32_e32 v106, s98
	v_mov_b32_e32 v107, s99
	v_readlane_b32 s98, v254, 25
	v_readlane_b32 s99, v254, 26
	v_mov_b32_e32 v108, s98
	v_mov_b32_e32 v109, s99
	v_readlane_b32 s100, v254, 22
	s_cmp_ge_u32 s100, 0x80
	s_cbranch_scc1 .Lrto_done
	v_lshrrev_b32_e32 v110, 6, v128
	v_and_b32_e32 v111, 15, v128
	v_bfe_u32 v112, v128, 4, 2
	v_lshl_or_b32 v113, v110, 4, v111
	v_add_u32_e32 v114, 0x8000, v113
	v_mul_u32_u24_e32 v114, 0x800, v114
	v_lshl_add_u32 v114, v112, 4, v114
	v_mul_u32_u24_e32 v115, 0x800, v111
	v_lshl_add_u32 v115, v112, 4, v115
	v_lshlrev_b32_e32 v116, 12, v113
	v_lshl_add_u32 v116, v112, 4, v116
	v_mov_b32_e32 v119, 0
.Lrto_loop:
	s_lshr_b32 s101, s100, 5
	s_and_b32 s98, s100, 31
	s_lshl_b32 s99, s101, 9
	s_mul_i32 vcc_lo, s98, 0x10000
	s_add_i32 vcc_lo, vcc_lo, s99
	v_add_u32_e32 v118, s99, v114
	v_lshl_add_u64 v[120:121], v[104:105], 0, v[118:119]
	v_add_u32_e32 v118, vcc_lo, v115
	v_lshl_add_u64 v[122:123], v[106:107], 0, v[118:119]
	v_add_u32_e32 v118, 0x8000, v118
	v_lshl_add_u64 v[124:125], v[106:107], 0, v[118:119]
	s_lshl_b32 s99, s101, 19
	s_lshl_b32 s98, s98, 7
	s_add_i32 s99, s99, s98
	v_add_u32_e32 v118, s99, v116
	v_lshl_add_u64 v[126:127], v[108:109], 0, v[118:119]
	global_load_dwordx4 v[64:67], v[120:121], off
	global_load_dwordx4 v[0:3], v[122:123], off
	global_load_dwordx4 v[32:35], v[124:125], off
	global_load_dwordx4 v[68:71], v[120:121], off offset:64
	global_load_dwordx4 v[4:7], v[122:123], off offset:64
	global_load_dwordx4 v[36:39], v[124:125], off offset:64
	global_load_dwordx4 v[72:75], v[120:121], off offset:128
	global_load_dwordx4 v[8:11], v[122:123], off offset:128
	global_load_dwordx4 v[40:43], v[124:125], off offset:128
	global_load_dwordx4 v[76:79], v[120:121], off offset:192
	global_load_dwordx4 v[12:15], v[122:123], off offset:192
	global_load_dwordx4 v[44:47], v[124:125], off offset:192
	global_load_dwordx4 v[80:83], v[120:121], off offset:256
	global_load_dwordx4 v[16:19], v[122:123], off offset:256
	global_load_dwordx4 v[48:51], v[124:125], off offset:256
	global_load_dwordx4 v[84:87], v[120:121], off offset:320
	global_load_dwordx4 v[20:23], v[122:123], off offset:320
	global_load_dwordx4 v[52:55], v[124:125], off offset:320
	global_load_dwordx4 v[88:91], v[120:121], off offset:384
	global_load_dwordx4 v[24:27], v[122:123], off offset:384
	global_load_dwordx4 v[56:59], v[124:125], off offset:384
	global_load_dwordx4 v[92:95], v[120:121], off offset:448
	global_load_dwordx4 v[28:31], v[122:123], off offset:448
	global_load_dwordx4 v[60:63], v[124:125], off offset:448
	s_waitcnt vmcnt(21)
	v_mfma_f32_16x16x32_bf16 v[96:99], v[0:3], v[64:67], 0
	v_mfma_f32_16x16x32_bf16 v[100:103], v[32:35], v[64:67], 0
	s_waitcnt vmcnt(18)
	v_mfma_f32_16x16x32_bf16 v[96:99], v[4:7], v[68:71], v[96:99]
	v_mfma_f32_16x16x32_bf16 v[100:103], v[36:39], v[68:71], v[100:103]
	s_waitcnt vmcnt(15)
	v_mfma_f32_16x16x32_bf16 v[96:99], v[8:11], v[72:75], v[96:99]
	v_mfma_f32_16x16x32_bf16 v[100:103], v[40:43], v[72:75], v[100:103]
	s_waitcnt vmcnt(12)
	v_mfma_f32_16x16x32_bf16 v[96:99], v[12:15], v[76:79], v[96:99]
	v_mfma_f32_16x16x32_bf16 v[100:103], v[44:47], v[76:79], v[100:103]
	s_waitcnt vmcnt(9)
	v_mfma_f32_16x16x32_bf16 v[96:99], v[16:19], v[80:83], v[96:99]
	v_mfma_f32_16x16x32_bf16 v[100:103], v[48:51], v[80:83], v[100:103]
	s_waitcnt vmcnt(6)
	v_mfma_f32_16x16x32_bf16 v[96:99], v[20:23], v[84:87], v[96:99]
	v_mfma_f32_16x16x32_bf16 v[100:103], v[52:55], v[84:87], v[100:103]
	s_waitcnt vmcnt(3)
	v_mfma_f32_16x16x32_bf16 v[96:99], v[24:27], v[88:91], v[96:99]
	v_mfma_f32_16x16x32_bf16 v[100:103], v[56:59], v[88:91], v[100:103]
	s_waitcnt vmcnt(0)
	v_mfma_f32_16x16x32_bf16 v[96:99], v[28:31], v[92:95], v[96:99]
	v_mfma_f32_16x16x32_bf16 v[100:103], v[60:63], v[92:95], v[100:103]
	s_nop 15
	s_nop 7
	global_store_dwordx4 v[126:127], v[96:99], off
	global_store_dwordx4 v[126:127], v[100:103], off offset:64
	s_add_i32 s100, s100, s52
	s_cmp_lt_u32 s100, 0x80
	s_cbranch_scc1 .Lrto_loop
; DEVI int otid() { int t = threadIdx.x; asm volatile("" : "+v"(t)); return t; }
;     __device__ __forceinline__ bool next(int i, Unit& u) const { if (i != 0 || c >= n) return false; u.pm = pm; u.pn = c & 3; return true; }
; #define PG8_WAIT_V(n) asm volatile("s_waitcnt vmcnt(" #n ")" ::: "memory")
; #define PG8_BAR __builtin_amdgcn_s_barrier()
; template <class Epi, class Sched, bool ALIGN_EPI = false, bool SP2 = false>
; __device__ __forceinline__ void gemm_phase(PG8_LAS unsigned char* lds, const Gemm g, const Sched& S, const Epi& E) {
;     const int tid = otid(), wid = __builtin_amdgcn_readfirstlane(tid >> 6), lane = tid & 63, wr = wid >> 2, wc = wid & 3, fr = lane & 15, fq = lane >> 4;
;     const int K = g.K, nt = K / BK;
;     unsigned voffA[2], voffB[2];
; #pragma unroll
;     for (int i = 0; i < 2; ++i) { int R, C; stage_rc(tid * 16 + i * 8192, R, C); const int Rb = Epi::PERM ? ((R & ~31) + perm32(R & 31)) : R;
;         voffA[i] = (unsigned)(R * g.lda + C) * 2u; voffB[i] = (unsigned)(Rb * g.ldb + C) * 2u; }
;     const size_t kstep = (size_t)(BK * 2);
;     const size_t hstepA = (size_t)HALF * g.lda * 2, hstepB = (size_t)HALF * g.ldb * 2;
;     const size_t tstepA = 2 * hstepA, tstepB = 2 * hstepB;
;     const unsigned ldsw = (unsigned)wid * 1024u;
;     const int aoff = lds_byte(wr * 64 + fr, fq * 8), boff = lds_byte(wc * 32 + fr, fq * 8);
;     ...
;     Unit cur, nxt; int ui = 0;
;     if (!S.next(0, cur)) return;
;     f32x4 acc[2][2][4][2];
; #pragma unroll
;     for (int a = 0; a < 2; ++a)
; #pragma unroll
;         for (int b = 0; b < 2; ++b)
; #pragma unroll
;             for (int m = 0; m < 4; ++m)
; #pragma unroll
;                 for (int n = 0; n < 2; ++n) acc[a][b][m][n] = (f32x4){0.f, 0.f, 0.f, 0.f};
;     bf16x8 At[4][2], B0[2][2], B1[2][2];
;     const char* cA = (const char*)g.A + (size_t)cur.pm * tstepA; const char* cB = (const char*)g.Bt + (size_t)cur.pn * tstepB;
;     S.a_ready(cur);
;     if constexpr (SP2) {
;         PG8_STAGE(PG8_SB(0, 0), cB, voffB); PG8_STAGE(PG8_SB(0, 1), cB + hstepB, voffB); PG8_STAGE(PG8_SA(0, 0), cA, voffA); PG8_STAGE(PG8_SA(0, 1), cA + hstepA, voffA);
;         if (wr == 1) PG8_BAR;
;         PG8_WAIT_V(2); PG8_BAR;
;         PG8_STAGE(PG8_SB(1, 0), cB + kstep, voffB); PG8_STAGE(PG8_SA(1, 0), cA + kstep, voffA); PG8_STAGE(PG8_SB(1, 1), cB + hstepB + kstep, voffB);
;         PG8_WAIT_V(6); PG8_BAR;
.Lrto_done:
	s_branch .LBB0_2028
	v_lshlrev_b32_e32 v0, 4, v20
	v_add_u32_e32 v1, 0x2000, v0
	v_ashrrev_i32_e32 v2, 31, v1
	v_lshrrev_b32_e32 v2, 22, v2
	v_add_u32_e32 v2, v1, v2
	v_ashrrev_i32_e32 v2, 10, v2
	v_mul_i32_i24_e32 v4, 0x400, v2
	v_sub_u32_e32 v1, v1, v4
	v_lshrrev_b32_e32 v4, 4, v1
	v_bitop3_b32 v1, v4, v1, 32 bitop3:0x6c
	v_ashrrev_i32_e32 v4, 31, v1
	v_lshrrev_b32_e32 v4, 26, v4
	v_add_u32_e32 v4, v1, v4
	v_lshrrev_b32_e32 v5, 6, v4
	v_and_b32_e32 v4, 0xc0, v4
	v_lshlrev_b32_e32 v3, 5, v2
	v_sub_u32_e32 v1, v1, v4
	v_and_b32_e32 v3, 32, v3
	v_ashrrev_i16_sdwa v1, v181, sext(v1) dst_sel:DWORD dst_unused:UNUSED_PAD src0_sel:DWORD src1_sel:BYTE_0
	v_add_u32_sdwa v1, v3, sext(v1) dst_sel:DWORD dst_unused:UNUSED_PAD src0_sel:DWORD src1_sel:WORD_0
	v_bfe_i32 v3, v20, 27, 1
	v_lshrrev_b32_e32 v3, 22, v3
	v_add_u32_e32 v3, v0, v3
	v_and_b32_e32 v3, 0xfffffc00, v3
	s_ashr_i32 s17, s0, 2
	v_lshlrev_b32_e32 v2, 3, v2
	v_sub_u32_e32 v0, v0, v3
	s_and_b32 s16, s0, 3
	s_lshl_b32 s0, s17, 8
	v_and_b32_e32 v2, 0x1ffff0, v2
	v_lshrrev_b32_e32 v3, 4, v0
	s_ashr_i32 s2, s45, 6
	s_ashr_i32 s1, s0, 31
	v_add_lshl_u32 v2, v5, v2, 11
	v_bitop3_b32 v3, v3, v0, 32 bitop3:0x6c
	v_ashrrev_i32_e32 v0, 31, v0
	s_ashr_i32 s18, s45, 8
	s_lshl_b32 s19, s2, 10
	s_lshl_b64 s[0:1], s[0:1], 1
	v_readlane_b32 s3, v254, 8
	v_lshl_add_u32 v4, v1, 1, v2
	v_ashrrev_i32_e32 v1, 31, v20
	v_lshrrev_b32_e32 v0, 26, v0
	s_add_u32 s3, s3, s0
	v_readlane_b32 s4, v254, 9
	v_lshrrev_b32_e32 v1, 26, v1
	v_add_u32_e32 v0, v3, v0
	s_addc_u32 s4, s4, s1
	v_readlane_b32 s6, v254, 18
	v_add_u32_e32 v1, v20, v1
	v_ashrrev_i32_e32 v0, 6, v0
	v_readlane_b32 s7, v254, 19
	s_add_u32 s46, s6, s0
	v_ashrrev_i32_e32 v1, 6, v1
	v_mul_i32_i24_e32 v5, 64, v0
	s_addc_u32 s47, s7, s1
	v_lshlrev_b32_e32 v2, 5, v1
	v_sub_u32_e32 v3, v3, v5
	v_lshlrev_b32_e32 v1, 3, v1
	s_lshl_b32 s0, s16, 19
	v_and_b32_e32 v2, 32, v2
	v_ashrrev_i16_sdwa v3, v181, sext(v3) dst_sel:DWORD dst_unused:UNUSED_PAD src0_sel:DWORD src1_sel:BYTE_0
	v_and_b32_e32 v1, 0x1ffff0, v1
	s_add_u32 s0, s3, s0
	v_add_u32_sdwa v2, v2, sext(v3) dst_sel:DWORD dst_unused:UNUSED_PAD src0_sel:DWORD src1_sel:WORD_0
	v_add_lshl_u32 v0, v0, v1, 11
	s_addc_u32 s1, s4, 0
	s_add_i32 s20, s19, 0x10000
	s_add_i32 s25, s19, 0x12000
	v_lshl_add_u32 v16, v2, 1, v0
	s_mov_b32 m0, s20
	s_add_u32 s4, s0, 0x40000
	global_load_lds_dwordx4 v16, s[0:1]
	s_mov_b32 m0, s25
	s_addc_u32 s5, s1, 0
	s_add_i32 s27, s19, 0x14000
	global_load_lds_dwordx4 v4, s[0:1]
	s_mov_b32 m0, s27
	s_add_i32 s36, s19, 0x16000
	v_mov_b32_e32 v17, v130
	v_mov_b32_e32 v5, v130
	global_load_lds_dwordx4 v16, s[4:5]
	s_mov_b32 m0, s36
	v_lshl_add_u64 v[6:7], s[4:5], 0, v[16:17]
	v_lshl_add_u64 v[10:11], s[4:5], 0, v[4:5]
	global_load_lds_dwordx4 v4, s[4:5]
	s_add_u32 s4, s46, 0x4000000
	s_addc_u32 s5, s47, 0
	s_mov_b32 m0, s19
	s_add_i32 s38, s19, 0x2000
	global_load_lds_dwordx4 v16, s[4:5]
	s_mov_b32 m0, s38
	v_lshl_add_u64 v[14:15], s[4:5], 0, v[16:17]
	v_lshl_add_u64 v[18:19], s[4:5], 0, v[4:5]
	global_load_lds_dwordx4 v4, s[4:5]
	s_add_u32 s4, s46, 0x4040000
	s_addc_u32 s5, s47, 0
	s_add_i32 s35, s19, 0x4000
	s_mov_b32 m0, s35
	s_add_i32 s37, s19, 0x6000
	global_load_lds_dwordx4 v16, s[4:5]
	s_mov_b32 m0, s37
	v_lshl_add_u64 v[0:1], s[0:1], 0, v[16:17]
	global_load_lds_dwordx4 v4, s[4:5]
	v_lshl_add_u64 v[2:3], s[0:1], 0, v[4:5]
	v_lshl_add_u64 v[8:9], s[4:5], 0, v[16:17]
	v_lshl_add_u64 v[12:13], s[4:5], 0, v[4:5]
	s_cmp_lg_u32 s18, 1
	s_cbranch_scc1 .LBB0_2025
	s_barrier

; #define PG8_LAS __attribute__((address_space(3)))
; DEVI int obid() { int t = blockIdx.x; asm volatile("" : "+s"(t)); return t; }
;     __device__ __forceinline__ void operator()(const f32x4 (&acc)[2][2][4][2], const Unit& u, int wr, int wc, int fr, int fq) const {
;         const int col0 = u.pn * BM + wc * 32 + 4 * fq;
; #pragma unroll
;         for (int m = 0; m < 4; ++m) { float* sp = slab + ((size_t)(ks * 128 + wr * 64 + m * 16 + fr)) * 1024 + col0;
; #pragma unroll
;             for (int bj = 0; bj < 2; ++bj)
; #pragma unroll
;                 for (int n = 0; n < 2; ++n) *(f32x4*)(sp + bj * HALF + n * 16) = acc[0][bj][m][n]; }
; template <bool FIRST>
; __device__ __forceinline__ void run_gemm_res(const Params& p, unsigned char* smem, const bf16_t* A, int lda, const bf16_t* Bt, int K) {
;     ...
;   { const int c = obid(), ks = c >> 2;
;     pg8::TailOrder TS{c, 4 * (K >> 8), 128};
;     pg8::Gemm g{A + ks * 256, Bt + ks * 256, MP, 1024, 256, lda, K};
;     pg8::gemm_phase<pg8::EpiSlab, pg8::TailOrder, true, true>((PG8_LAS unsigned char*)smem, g, TS, pg8::EpiSlab{(float*)(p.ws + OFF_SLAB), ks}); }
.LBB0_2406:
	v_readlane_b32 s0, v254, 22
	v_mov_b32_e32 v20, v128
	s_cmp_gt_i32 s0, 63
	v_readfirstlane_b32 s47, v20
	v_mov_b32_e32 v104, s60
	v_mov_b32_e32 v105, s61
	v_mov_b32_e32 v106, s59
	v_mov_b32_e32 v107, s35
	v_readlane_b32 s98, v254, 25
	v_readlane_b32 s99, v254, 26
	v_mov_b32_e32 v108, s98
	v_mov_b32_e32 v109, s99
	v_readlane_b32 s100, v254, 22
	s_cmp_ge_u32 s100, 0x200
	s_cbranch_scc1 .Lrtf_done
	v_lshrrev_b32_e32 v110, 6, v128
	v_and_b32_e32 v111, 15, v128
	v_bfe_u32 v112, v128, 4, 2
	v_lshl_or_b32 v113, v110, 4, v111
	v_add_u32_e32 v114, 0x8000, v113
	v_mul_u32_u24_e32 v114, 0x2000, v114
	v_lshl_add_u32 v114, v112, 4, v114
	v_mul_u32_u24_e32 v115, 0x2000, v111
	v_lshl_add_u32 v115, v112, 4, v115
	v_lshlrev_b32_e32 v116, 12, v113
	v_lshl_add_u32 v116, v112, 4, v116
	v_mov_b32_e32 v119, 0
.Lrtf_loop:
	s_lshr_b32 s101, s100, 5
	s_and_b32 s98, s100, 31
	s_lshl_b32 s99, s101, 9
	s_mul_i32 vcc_lo, s98, 0x40000
	s_add_i32 vcc_lo, vcc_lo, s99
	v_add_u32_e32 v118, s99, v114
	v_lshl_add_u64 v[120:121], v[104:105], 0, v[118:119]
	v_add_u32_e32 v118, vcc_lo, v115
	v_lshl_add_u64 v[122:123], v[106:107], 0, v[118:119]
	v_add_u32_e32 v118, 0x20000, v118
	v_lshl_add_u64 v[124:125], v[106:107], 0, v[118:119]
	s_lshl_b32 s99, s101, 19
	s_lshl_b32 s98, s98, 7
	s_add_i32 s99, s99, s98
	v_add_u32_e32 v118, s99, v116
	v_lshl_add_u64 v[126:127], v[108:109], 0, v[118:119]
	global_load_dwordx4 v[64:67], v[120:121], off
	global_load_dwordx4 v[0:3], v[122:123], off
	global_load_dwordx4 v[32:35], v[124:125], off
	global_load_dwordx4 v[68:71], v[120:121], off offset:64
	global_load_dwordx4 v[4:7], v[122:123], off offset:64
	global_load_dwordx4 v[36:39], v[124:125], off offset:64
	global_load_dwordx4 v[72:75], v[120:121], off offset:128
	global_load_dwordx4 v[8:11], v[122:123], off offset:128
	global_load_dwordx4 v[40:43], v[124:125], off offset:128
	global_load_dwordx4 v[76:79], v[120:121], off offset:192
	global_load_dwordx4 v[12:15], v[122:123], off offset:192
	global_load_dwordx4 v[44:47], v[124:125], off offset:192
	global_load_dwordx4 v[80:83], v[120:121], off offset:256
	global_load_dwordx4 v[16:19], v[122:123], off offset:256
	global_load_dwordx4 v[48:51], v[124:125], off offset:256
	global_load_dwordx4 v[84:87], v[120:121], off offset:320
	global_load_dwordx4 v[20:23], v[122:123], off offset:320
	global_load_dwordx4 v[52:55], v[124:125], off offset:320
	global_load_dwordx4 v[88:91], v[120:121], off offset:384
	global_load_dwordx4 v[24:27], v[122:123], off offset:384
	global_load_dwordx4 v[56:59], v[124:125], off offset:384
	global_load_dwordx4 v[92:95], v[120:121], off offset:448
	global_load_dwordx4 v[28:31], v[122:123], off offset:448
	global_load_dwordx4 v[60:63], v[124:125], off offset:448
	s_waitcnt vmcnt(21)
	v_mfma_f32_16x16x32_bf16 v[96:99], v[0:3], v[64:67], 0
	v_mfma_f32_16x16x32_bf16 v[100:103], v[32:35], v[64:67], 0
	s_waitcnt vmcnt(18)
	v_mfma_f32_16x16x32_bf16 v[96:99], v[4:7], v[68:71], v[96:99]
	v_mfma_f32_16x16x32_bf16 v[100:103], v[36:39], v[68:71], v[100:103]
	s_waitcnt vmcnt(15)
	v_mfma_f32_16x16x32_bf16 v[96:99], v[8:11], v[72:75], v[96:99]
	v_mfma_f32_16x16x32_bf16 v[100:103], v[40:43], v[72:75], v[100:103]
	s_waitcnt vmcnt(12)
	v_mfma_f32_16x16x32_bf16 v[96:99], v[12:15], v[76:79], v[96:99]
	v_mfma_f32_16x16x32_bf16 v[100:103], v[44:47], v[76:79], v[100:103]
	s_waitcnt vmcnt(9)
	v_mfma_f32_16x16x32_bf16 v[96:99], v[16:19], v[80:83], v[96:99]
	v_mfma_f32_16x16x32_bf16 v[100:103], v[48:51], v[80:83], v[100:103]
	s_waitcnt vmcnt(6)
	v_mfma_f32_16x16x32_bf16 v[96:99], v[20:23], v[84:87], v[96:99]
	v_mfma_f32_16x16x32_bf16 v[100:103], v[52:55], v[84:87], v[100:103]
	s_waitcnt vmcnt(3)
	v_mfma_f32_16x16x32_bf16 v[96:99], v[24:27], v[88:91], v[96:99]
	v_mfma_f32_16x16x32_bf16 v[100:103], v[56:59], v[88:91], v[100:103]
	s_waitcnt vmcnt(0)
	v_mfma_f32_16x16x32_bf16 v[96:99], v[28:31], v[92:95], v[96:99]
	v_mfma_f32_16x16x32_bf16 v[100:103], v[60:63], v[92:95], v[100:103]
	s_nop 15
	s_nop 7
	global_store_dwordx4 v[126:127], v[96:99], off
	global_store_dwordx4 v[126:127], v[100:103], off offset:64
	s_add_i32 s100, s100, s52
	s_cmp_lt_u32 s100, 0x200
	s_cbranch_scc1 .Lrtf_loop
; DEVI int otid() { int t = threadIdx.x; asm volatile("" : "+v"(t)); return t; }
;     __device__ __forceinline__ bool next(int i, Unit& u) const { if (i != 0 || c >= n) return false; u.pm = pm; u.pn = c & 3; return true; }
; #define PG8_WAIT_V(n) asm volatile("s_waitcnt vmcnt(" #n ")" ::: "memory")
; #define PG8_BAR __builtin_amdgcn_s_barrier()
; template <class Epi, class Sched, bool ALIGN_EPI = false, bool SP2 = false>
; __device__ __forceinline__ void gemm_phase(PG8_LAS unsigned char* lds, const Gemm g, const Sched& S, const Epi& E) {
;     const int tid = otid(), wid = __builtin_amdgcn_readfirstlane(tid >> 6), lane = tid & 63, wr = wid >> 2, wc = wid & 3, fr = lane & 15, fq = lane >> 4;
;     const int K = g.K, nt = K / BK;
;     unsigned voffA[2], voffB[2];
; #pragma unroll
;     for (int i = 0; i < 2; ++i) { int R, C; stage_rc(tid * 16 + i * 8192, R, C); const int Rb = Epi::PERM ? ((R & ~31) + perm32(R & 31)) : R;
;         voffA[i] = (unsigned)(R * g.lda + C) * 2u; voffB[i] = (unsigned)(Rb * g.ldb + C) * 2u; }
;     const size_t kstep = (size_t)(BK * 2);
;     const size_t hstepA = (size_t)HALF * g.lda * 2, hstepB = (size_t)HALF * g.ldb * 2;
;     const size_t tstepA = 2 * hstepA, tstepB = 2 * hstepB;
;     const unsigned ldsw = (unsigned)wid * 1024u;
;     const int aoff = lds_byte(wr * 64 + fr, fq * 8), boff = lds_byte(wc * 32 + fr, fq * 8);
;     ...
;     Unit cur, nxt; int ui = 0;
;     if (!S.next(0, cur)) return;
;     f32x4 acc[2][2][4][2];
; #pragma unroll
;     for (int a = 0; a < 2; ++a)
; #pragma unroll
;         for (int b = 0; b < 2; ++b)
; #pragma unroll
;             for (int m = 0; m < 4; ++m)
; #pragma unroll
;                 for (int n = 0; n < 2; ++n) acc[a][b][m][n] = (f32x4){0.f, 0.f, 0.f, 0.f};
;     bf16x8 At[4][2], B0[2][2], B1[2][2];
;     const char* cA = (const char*)g.A + (size_t)cur.pm * tstepA; const char* cB = (const char*)g.Bt + (size_t)cur.pn * tstepB;
;     S.a_ready(cur);
;     if constexpr (SP2) {
;         PG8_STAGE(PG8_SB(0, 0), cB, voffB); PG8_STAGE(PG8_SB(0, 1), cB + hstepB, voffB); PG8_STAGE(PG8_SA(0, 0), cA, voffA); PG8_STAGE(PG8_SA(0, 1), cA + hstepA, voffA);
;         if (wr == 1) PG8_BAR;
;         PG8_WAIT_V(2); PG8_BAR;
;         PG8_STAGE(PG8_SB(1, 0), cB + kstep, voffB); PG8_STAGE(PG8_SA(1, 0), cA + kstep, voffA); PG8_STAGE(PG8_SB(1, 1), cB + hstepB + kstep, voffB);
;         PG8_WAIT_V(6); PG8_BAR;
.Lrtf_done:
	s_branch .LBB0_2412
	v_lshlrev_b32_e32 v0, 4, v20
	v_add_u32_e32 v1, 0x2000, v0
	v_ashrrev_i32_e32 v2, 31, v1
	v_lshrrev_b32_e32 v2, 22, v2
	v_add_u32_e32 v2, v1, v2
	v_ashrrev_i32_e32 v2, 10, v2
	v_mul_i32_i24_e32 v4, 0x400, v2
	v_sub_u32_e32 v1, v1, v4
	v_lshrrev_b32_e32 v4, 4, v1
	v_bitop3_b32 v1, v4, v1, 32 bitop3:0x6c
	v_ashrrev_i32_e32 v4, 31, v1
	v_lshrrev_b32_e32 v4, 26, v4
	v_add_u32_e32 v4, v1, v4
	v_lshrrev_b32_e32 v5, 6, v4
	v_and_b32_e32 v4, 0xc0, v4
	v_lshlrev_b32_e32 v3, 5, v2
	v_sub_u32_e32 v1, v1, v4
	v_and_b32_e32 v3, 32, v3
	v_ashrrev_i16_sdwa v1, v181, sext(v1) dst_sel:DWORD dst_unused:UNUSED_PAD src0_sel:DWORD src1_sel:BYTE_0
	v_add_u32_sdwa v1, v3, sext(v1) dst_sel:DWORD dst_unused:UNUSED_PAD src0_sel:DWORD src1_sel:WORD_0
	v_bfe_i32 v3, v20, 27, 1
	v_lshrrev_b32_e32 v3, 22, v3
	v_add_u32_e32 v3, v0, v3
	v_and_b32_e32 v3, 0xfffffc00, v3
	s_ashr_i32 s19, s0, 2
	v_lshlrev_b32_e32 v2, 3, v2
	v_sub_u32_e32 v0, v0, v3
	s_and_b32 s18, s0, 3
	s_lshl_b32 s0, s19, 8
	v_and_b32_e32 v2, 0x7fff0, v2
	v_lshrrev_b32_e32 v3, 4, v0
	s_ashr_i32 s2, s47, 6
	s_ashr_i32 s1, s0, 31
	v_add_lshl_u32 v2, v5, v2, 13
	v_bitop3_b32 v3, v3, v0, 32 bitop3:0x6c
	v_ashrrev_i32_e32 v0, 31, v0
	s_ashr_i32 s20, s47, 8
	s_lshl_b32 s21, s2, 10
	s_lshl_b64 s[0:1], s[0:1], 1
	v_lshl_add_u32 v4, v1, 1, v2
	v_ashrrev_i32_e32 v1, 31, v20
	v_lshrrev_b32_e32 v0, 26, v0
	s_add_u32 s3, s59, s0
	v_lshrrev_b32_e32 v1, 26, v1
	v_add_u32_e32 v0, v3, v0
	s_addc_u32 s4, s35, s1
	v_add_u32_e32 v1, v20, v1
	v_ashrrev_i32_e32 v0, 6, v0
	s_add_u32 s58, s60, s0
	v_ashrrev_i32_e32 v1, 6, v1
	v_mul_i32_i24_e32 v5, 64, v0
	s_addc_u32 s59, s61, s1
	v_lshlrev_b32_e32 v2, 5, v1
	v_sub_u32_e32 v3, v3, v5
	v_lshlrev_b32_e32 v1, 3, v1
	s_lshl_b32 s0, s18, 21
	v_and_b32_e32 v2, 32, v2
	v_ashrrev_i16_sdwa v3, v181, sext(v3) dst_sel:DWORD dst_unused:UNUSED_PAD src0_sel:DWORD src1_sel:BYTE_0
	v_and_b32_e32 v1, 0x7fff0, v1
	s_add_u32 s0, s3, s0
	v_add_u32_sdwa v2, v2, sext(v3) dst_sel:DWORD dst_unused:UNUSED_PAD src0_sel:DWORD src1_sel:WORD_0
	v_add_lshl_u32 v0, v0, v1, 13
	s_addc_u32 s1, s4, 0
	s_add_i32 s25, s21, 0x10000
	s_add_i32 s35, s21, 0x12000
	v_lshl_add_u32 v16, v2, 1, v0
	s_mov_b32 m0, s25
	s_add_u32 s4, s0, 0x100000
	global_load_lds_dwordx4 v16, s[0:1]
	s_mov_b32 m0, s35
	s_addc_u32 s5, s1, 0
	s_add_i32 s36, s21, 0x14000
	global_load_lds_dwordx4 v4, s[0:1]
	s_mov_b32 m0, s36
	s_add_i32 s38, s21, 0x16000
	v_mov_b32_e32 v17, v130
	v_mov_b32_e32 v5, v130
	global_load_lds_dwordx4 v16, s[4:5]
	s_mov_b32 m0, s38
	v_lshl_add_u64 v[6:7], s[4:5], 0, v[16:17]
	v_lshl_add_u64 v[10:11], s[4:5], 0, v[4:5]
	global_load_lds_dwordx4 v4, s[4:5]
	s_add_u32 s4, s58, 0x10000000
	s_addc_u32 s5, s59, 0
	s_mov_b32 m0, s21
	s_add_i32 s40, s21, 0x2000
	global_load_lds_dwordx4 v16, s[4:5]
	s_mov_b32 m0, s40
	v_lshl_add_u64 v[14:15], s[4:5], 0, v[16:17]
	v_lshl_add_u64 v[18:19], s[4:5], 0, v[4:5]
	global_load_lds_dwordx4 v4, s[4:5]
	s_add_u32 s4, s58, 0x10100000
	s_addc_u32 s5, s59, 0
	s_add_i32 s37, s21, 0x4000
	s_mov_b32 m0, s37
	s_add_i32 s39, s21, 0x6000
	global_load_lds_dwordx4 v16, s[4:5]
	s_mov_b32 m0, s39
	v_lshl_add_u64 v[0:1], s[0:1], 0, v[16:17]
	global_load_lds_dwordx4 v4, s[4:5]
	v_lshl_add_u64 v[2:3], s[0:1], 0, v[4:5]
	v_lshl_add_u64 v[8:9], s[4:5], 0, v[16:17]
	v_lshl_add_u64 v[12:13], s[4:5], 0, v[4:5]
	s_cmp_lg_u32 s20, 1
	s_cbranch_scc1 .LBB0_2409
	s_barrier
